# v39 + sc1 (write-through) on the norm1 phase's H stores
# speedup vs baseline: 1.0105x; 1.0010x over previous
; __global__ void __launch_bounds__(NWAVES * 64, 2) fwd_kernel(Args args_unused) {
;     ...
;         { const int nrow = grouped ? (4 * SEQ + 4 * CTXL) : MT;
;           for (int r = gw; r < nrow; r += NGW) { const int mrow = (!grouped || r < 4 * SEQ) ? r : ML + (r - 4 * SEQ); P1_ROW(mrow); } }
.LBB0_173:
	v_lshl_add_u64 v[30:31], s[20:21], 0, v[4:5]
	global_load_dwordx4 v[14:17], v[30:31], off nt
	global_load_dwordx4 v[18:21], v[30:31], off offset:1024 nt
	global_load_dwordx4 v[22:25], v[30:31], off offset:3072 nt
	global_load_dwordx4 v[26:29], v[30:31], off offset:2048 nt
	s_min_i32 s8, s16, 0x8000
	s_ashr_i32 s8, s8, 12
	s_mul_hi_i32 s21, s8, 0x6000
	s_mulk_i32 s8, 0x6000
	s_add_u32 s20, s12, s8
	s_addc_u32 s21, s13, s21
	v_lshl_add_u64 v[54:55], s[20:21], 0, v[4:5]
	v_add_co_u32_e32 v30, vcc, s3, v54
	v_lshl_add_u64 v[56:57], v[54:55], 0, s[14:15]
	s_nop 0
	v_addc_co_u32_e32 v31, vcc, 0, v55, vcc
	global_load_dwordx4 v[30:33], v[30:31], off nt
	s_nop 0
	global_load_dwordx4 v[34:37], v[56:57], off offset:1024 nt
	global_load_dwordx4 v[38:41], v[2:3], off offset:1024 nt
	global_load_dwordx4 v[42:45], v[2:3], off nt
	global_load_dwordx4 v[46:49], v[54:55], off offset:1024 nt
	global_load_dwordx4 v[50:53], v[54:55], off nt
	s_lshl_b64 s[16:17], s[16:17], 11
	s_add_i32 s23, s23, s24
	s_cmp_ge_i32 s23, s0
	s_waitcnt vmcnt(9)
	v_pk_mul_f32 v[58:59], v[16:17], v[16:17]
	v_pk_mul_f32 v[60:61], v[14:15], v[14:15]
	s_waitcnt vmcnt(8)
	v_pk_mul_f32 v[62:63], v[20:21], v[20:21]
	v_pk_mul_f32 v[64:65], v[18:19], v[18:19]
	v_pk_mov_b32 v[70:71], v[60:61], v[58:59] op_sel:[1,0]
	v_mov_b32_e32 v61, v59
	v_pk_mov_b32 v[58:59], v[64:65], v[62:63] op_sel:[1,0]
	v_mov_b32_e32 v65, v63
	s_waitcnt vmcnt(7)
	v_mul_f32_e32 v69, v23, v23
	s_waitcnt vmcnt(6)
	v_mul_f32_e32 v66, v27, v27
	v_mul_f32_e32 v68, v29, v29
	v_pk_add_f32 v[60:61], v[70:71], v[60:61]
	v_pk_add_f32 v[58:59], v[58:59], v[64:65]
	v_mul_f32_e32 v13, v22, v22
	v_mul_f32_e32 v72, v24, v24
	v_mul_f32_e32 v73, v25, v25
	v_pk_fma_f32 v[62:63], v[26:27], v[26:27], v[66:67] op_sel_hi:[1,1,0]
	v_pk_fma_f32 v[66:67], v[28:29], v[28:29], v[68:69] op_sel_hi:[1,1,0]
	v_pk_add_f32 v[60:61], v[60:61], v[60:61] op_sel:[0,1] op_sel_hi:[1,0]
	v_pk_add_f32 v[58:59], v[58:59], v[58:59] op_sel:[0,1] op_sel_hi:[1,0]
	v_mov_b32_e32 v63, v72
	v_mov_b32_e32 v67, v73
	v_mov_b32_e32 v61, v13
	v_mov_b32_e32 v59, v69
	v_pk_add_f32 v[62:63], v[62:63], v[66:67]
	v_pk_add_f32 v[58:59], v[60:61], v[58:59]
	s_waitcnt vmcnt(5)
	v_pk_add_f32 v[32:33], v[32:33], 1.0 op_sel_hi:[1,0]
	v_pk_add_f32 v[58:59], v[58:59], v[62:63]
	v_pk_add_f32 v[30:31], v[30:31], 1.0 op_sel_hi:[1,0]
	v_add_f32_e32 v13, v58, v59
	ds_bpermute_b32 v58, v6, v13
	s_waitcnt vmcnt(4)
	v_pk_add_f32 v[36:37], v[36:37], 1.0 op_sel_hi:[1,0]
	v_pk_add_f32 v[34:35], v[34:35], 1.0 op_sel_hi:[1,0]
	s_waitcnt lgkmcnt(0)
	v_add_f32_e32 v13, v13, v58
	ds_bpermute_b32 v58, v7, v13
	s_waitcnt lgkmcnt(0)
	v_add_f32_e32 v13, v13, v58
	ds_bpermute_b32 v58, v8, v13
	s_waitcnt lgkmcnt(0)
	v_add_f32_e32 v13, v13, v58
	ds_bpermute_b32 v58, v9, v13
	s_waitcnt lgkmcnt(0)
	v_add_f32_e32 v13, v13, v58
	ds_bpermute_b32 v58, v10, v13
	s_waitcnt lgkmcnt(0)
	v_add_f32_e32 v13, v13, v58
	ds_bpermute_b32 v60, v11, v13
	v_lshl_add_u64 v[58:59], v[0:1], 0, s[16:17]
	s_waitcnt lgkmcnt(0)
	v_add_f32_e32 v13, v13, v60
	v_fmamk_f32 v13, v13, 0x3a800000, v12
	v_mul_f32_e32 v60, 0x4b800000, v13
	v_cmp_gt_f32_e32 vcc, s1, v13
	s_nop 1
	v_cndmask_b32_e32 v13, v13, v60, vcc
	v_rsq_f32_e32 v13, v13
	s_nop 0
	v_mul_f32_e32 v60, 0x45800000, v13
	v_cndmask_b32_e32 v60, v13, v60, vcc
	v_pk_mul_f32 v[16:17], v[60:61], v[16:17] op_sel_hi:[0,1]
	v_pk_mul_f32 v[14:15], v[60:61], v[14:15] op_sel_hi:[0,1]
	v_pk_mul_f32 v[20:21], v[60:61], v[20:21] op_sel_hi:[0,1]
	v_pk_mul_f32 v[18:19], v[60:61], v[18:19] op_sel_hi:[0,1]
	s_waitcnt vmcnt(2)
	v_pk_mul_f32 v[14:15], v[42:43], v[14:15]
	v_pk_mul_f32 v[16:17], v[44:45], v[16:17]
	v_pk_mul_f32 v[18:19], v[38:39], v[18:19]
	v_pk_mul_f32 v[20:21], v[40:41], v[20:21]
	s_waitcnt vmcnt(0)
	v_pk_fma_f32 v[16:17], v[32:33], v[16:17], v[52:53]
	v_pk_fma_f32 v[14:15], v[30:31], v[14:15], v[50:51]
	v_pk_fma_f32 v[20:21], v[36:37], v[20:21], v[48:49]
	v_pk_fma_f32 v[18:19], v[34:35], v[18:19], v[46:47]
	v_cvt_pk_bf16_f32 v14, v14, v15
	v_cvt_pk_bf16_f32 v15, v16, v17
	v_cvt_pk_bf16_f32 v16, v18, v19
	v_cvt_pk_bf16_f32 v17, v20, v21
	global_store_dwordx2 v[58:59], v[14:15], off sc1
	global_store_dwordx2 v[58:59], v[16:17], off offset:512 sc1
	global_load_dwordx4 v[14:17], v[56:57], off offset:2048 nt
	s_nop 0
	global_load_dwordx4 v[18:21], v[2:3], off offset:2048 nt
	global_load_dwordx4 v[30:33], v[56:57], off offset:3072 nt
	global_load_dwordx4 v[34:37], v[2:3], off offset:3072 nt
	global_load_dwordx4 v[38:41], v[54:55], off offset:2048 nt
	global_load_dwordx4 v[42:45], v[54:55], off offset:3072 nt
	v_pk_mul_f32 v[28:29], v[60:61], v[28:29] op_sel_hi:[0,1]
	v_pk_mul_f32 v[26:27], v[60:61], v[26:27] op_sel_hi:[0,1]
	v_pk_mul_f32 v[24:25], v[60:61], v[24:25] op_sel_hi:[0,1]
	v_pk_mul_f32 v[22:23], v[60:61], v[22:23] op_sel_hi:[0,1]
	s_waitcnt vmcnt(5)
	v_pk_add_f32 v[16:17], v[16:17], 1.0 op_sel_hi:[1,0]
	v_pk_add_f32 v[14:15], v[14:15], 1.0 op_sel_hi:[1,0]
	s_waitcnt vmcnt(4)
	v_pk_mul_f32 v[18:19], v[18:19], v[26:27]
	v_pk_mul_f32 v[20:21], v[20:21], v[28:29]
	s_waitcnt vmcnt(3)
	v_pk_add_f32 v[26:27], v[32:33], 1.0 op_sel_hi:[1,0]
	v_pk_add_f32 v[28:29], v[30:31], 1.0 op_sel_hi:[1,0]
	s_waitcnt vmcnt(2)
	v_pk_mul_f32 v[22:23], v[34:35], v[22:23]
	v_pk_mul_f32 v[24:25], v[36:37], v[24:25]
	s_waitcnt vmcnt(1)
	v_pk_fma_f32 v[16:17], v[16:17], v[20:21], v[40:41]
	v_pk_fma_f32 v[14:15], v[14:15], v[18:19], v[38:39]
	s_waitcnt vmcnt(0)
	v_pk_fma_f32 v[18:19], v[26:27], v[24:25], v[44:45]
	v_pk_fma_f32 v[20:21], v[28:29], v[22:23], v[42:43]
	v_cvt_pk_bf16_f32 v14, v14, v15
	v_cvt_pk_bf16_f32 v15, v16, v17
	v_cvt_pk_bf16_f32 v16, v20, v21
	v_cvt_pk_bf16_f32 v17, v18, v19
	global_store_dwordx2 v[58:59], v[14:15], off offset:1024 sc1
	global_store_dwordx2 v[58:59], v[16:17], off offset:1536 sc1
	s_cbranch_scc1 .LBB0_178
